# E59: E52 plus MLA attention K fragments read one k-step ahead using the unused v[246:253] as a second fragment pair
# baseline (speedup 1.0000x reference)
; #define PK4(P, BASE, OUT) do { u32x4 w = {cvtb(P[BASE + 0], P[BASE + 1]), cvtb(P[BASE + 2], P[BASE + 3]), \
;     cvtb(P[BASE + 4], P[BASE + 5]), cvtb(P[BASE + 6], P[BASE + 7])}; OUT = *reinterpret_cast<bf16x8*>(&w); } while (0)
; __device__ __forceinline__ void finishSM(f32x16& p0, f32x16& p1, float alpha, float& l_reg, bf16x8& pa0, bf16x8& pa1, bf16x8& pa2, bf16x8& pa3) {
; #pragma unroll
;   for (int r = 0; r < 16; ++r) p1[r] = __builtin_amdgcn_exp2f(p1[r]);
;   float ps = 0;
; #pragma unroll
;   for (int r = 0; r < 16; ++r) ps += p0[r];
; #pragma unroll
;   for (int r = 0; r < 16; ++r) ps += p1[r];
;   { auto rr = __builtin_amdgcn_permlane32_swap(__float_as_uint(ps), __float_as_uint(ps), false, false);
;     ps = __uint_as_float(rr[0]) + __uint_as_float(rr[1]); }
;   l_reg = l_reg * alpha + ps;
;     ...
;   PK4(p0, 0, pa0); PK4(p0, 8, pa1); PK4(p1, 0, pa2); PK4(p1, 8, pa3);
;     ...
; }
; template <int NQK>
; __device__ __forceinline__ void qkt(f32x16& p0, f32x16& p1, const char* Ks, const bf16x8* qr, int r32, int hi) {
;   constexpr int KROW = NQK * 32 + 16;
;   p0 = f32x16{}; p1 = f32x16{};
; #pragma unroll
;   for (int d0 = 0; d0 < NQK; ++d0) { const int cb = (d0 * 16 + hi * 8) * 2;
;     bf16x8 b0 = *reinterpret_cast<const bf16x8*>(Ks + r32 * KROW + cb);
;     bf16x8 b1 = *reinterpret_cast<const bf16x8*>(Ks + (32 + r32) * KROW + cb);
;     p0 = __builtin_amdgcn_mfma_f32_32x32x16_bf16(b0, qr[d0], p0, 0, 0, 0);
;     p1 = __builtin_amdgcn_mfma_f32_32x32x16_bf16(b1, qr[d0], p1, 0, 0, 0); }
; }
.LBB0_2539:
	s_mov_b32 s14, s44
	s_mov_b32 s44, s8
	s_mul_i32 s8, s14, 0x6400
	v_add_u32_e32 v169, s8, v174
	ds_read_b128 v[64:67], v169 offset:61952
	ds_read_b128 v[68:71], v169 offset:49152
	ds_read_b128 v[180:183], v169 offset:49184
	ds_read_b128 v[222:225], v169 offset:61984
	ds_read_b128 v[246:249], v169 offset:49216
	ds_read_b128 v[250:253], v169 offset:62016
	v_exp_f32_e32 v231, v146
	v_add_f32_e32 v146, 0, v184
	s_waitcnt lgkmcnt(4)
	v_mfma_f32_32x32x16_bf16 v[80:95], v[68:71], v[140:143], 0
	v_add_f32_e32 v146, v185, v146
	v_add_f32_e32 v146, v189, v146
	v_add_f32_e32 v146, v191, v146
	v_add_f32_e32 v146, v198, v146
	v_add_f32_e32 v146, v200, v146
	v_add_f32_e32 v146, v214, v146
	v_add_f32_e32 v146, v217, v146
	v_mfma_f32_32x32x16_bf16 v[64:79], v[64:67], v[140:143], 0
	v_add_f32_e32 v146, v215, v146
	v_add_f32_e32 v146, v218, v146
	v_add_f32_e32 v146, v199, v146
	v_add_f32_e32 v146, v201, v146
	v_add_f32_e32 v146, v216, v146
	v_add_f32_e32 v146, v219, v146
	v_add_f32_e32 v146, v220, v146
	s_waitcnt lgkmcnt(3)
	v_mfma_f32_32x32x16_bf16 v[80:95], v[180:183], v[136:139], v[80:95]
	v_add_f32_e32 v146, v221, v146
	v_exp_f32_e32 v229, v150
	v_exp_f32_e32 v226, v155
	v_exp_f32_e32 v227, v152
	v_exp_f32_e32 v228, v153
	v_exp_f32_e32 v230, v151
	v_exp_f32_e32 v148, v148
	s_waitcnt lgkmcnt(2)
	v_mfma_f32_32x32x16_bf16 v[64:79], v[222:225], v[136:139], v[64:79]
	ds_read_b128 v[180:183], v169 offset:49248
	ds_read_b128 v[222:225], v169 offset:62048
	v_exp_f32_e32 v149, v149
	v_exp_f32_e32 v232, v147
	v_cvt_pk_bf16_f32 v155, v199, v201
	v_cvt_pk_bf16_f32 v147, v229, v230
	s_waitcnt lgkmcnt(3)
	v_mfma_f32_32x32x16_bf16 v[80:95], v[246:249], v[132:135], v[80:95]
	s_waitcnt lgkmcnt(2)
	v_mfma_f32_32x32x16_bf16 v[64:79], v[250:253], v[132:135], v[64:79]
	ds_read_b128 v[246:249], v169 offset:49280
	ds_read_b128 v[250:253], v169 offset:62080
	s_waitcnt lgkmcnt(3)
	v_mfma_f32_32x32x16_bf16 v[80:95], v[180:183], v[128:131], v[80:95]
	s_waitcnt lgkmcnt(2)
	v_mfma_f32_32x32x16_bf16 v[64:79], v[222:225], v[128:131], v[64:79]
	ds_read_b128 v[180:183], v169 offset:49312
	ds_read_b128 v[222:225], v169 offset:62112
	s_waitcnt lgkmcnt(3)
	v_mfma_f32_32x32x16_bf16 v[80:95], v[246:249], v[124:127], v[80:95]
	s_waitcnt lgkmcnt(2)
	v_mfma_f32_32x32x16_bf16 v[64:79], v[250:253], v[124:127], v[64:79]
	ds_read_b128 v[246:249], v169 offset:49344
	ds_read_b128 v[250:253], v169 offset:62144
	s_waitcnt lgkmcnt(3)
	v_mfma_f32_32x32x16_bf16 v[80:95], v[180:183], v[120:123], v[80:95]
	s_waitcnt lgkmcnt(2)
	v_mfma_f32_32x32x16_bf16 v[64:79], v[222:225], v[120:123], v[64:79]
	ds_read_b128 v[180:183], v169 offset:49376
	ds_read_b128 v[222:225], v169 offset:62176
	s_waitcnt lgkmcnt(3)
	v_mfma_f32_32x32x16_bf16 v[80:95], v[246:249], v[116:119], v[80:95]
	s_waitcnt lgkmcnt(2)
	v_mfma_f32_32x32x16_bf16 v[64:79], v[250:253], v[116:119], v[64:79]
	ds_read_b128 v[246:249], v169 offset:49408
	ds_read_b128 v[250:253], v169 offset:62208
	s_waitcnt lgkmcnt(3)
	v_mfma_f32_32x32x16_bf16 v[80:95], v[180:183], v[112:115], v[80:95]
	s_waitcnt lgkmcnt(2)
	v_mfma_f32_32x32x16_bf16 v[64:79], v[222:225], v[112:115], v[64:79]
	ds_read_b128 v[180:183], v169 offset:49440
	ds_read_b128 v[222:225], v169 offset:62240
	s_waitcnt lgkmcnt(3)
	v_mfma_f32_32x32x16_bf16 v[80:95], v[246:249], v[108:111], v[80:95]
	s_waitcnt lgkmcnt(2)
	v_mfma_f32_32x32x16_bf16 v[64:79], v[250:253], v[108:111], v[64:79]
	ds_read_b128 v[246:249], v169 offset:49472
	ds_read_b128 v[250:253], v169 offset:62272
	s_waitcnt lgkmcnt(3)
	v_mfma_f32_32x32x16_bf16 v[80:95], v[180:183], v[104:107], v[80:95]
	s_waitcnt lgkmcnt(2)
	v_mfma_f32_32x32x16_bf16 v[64:79], v[222:225], v[104:107], v[64:79]
	ds_read_b128 v[180:183], v169 offset:49504
	ds_read_b128 v[222:225], v169 offset:62304
	s_waitcnt lgkmcnt(3)
	v_mfma_f32_32x32x16_bf16 v[80:95], v[246:249], v[100:103], v[80:95]
	s_waitcnt lgkmcnt(2)
	v_mfma_f32_32x32x16_bf16 v[64:79], v[250:253], v[100:103], v[64:79]
	v_exp_f32_e32 v169, v160
	v_cvt_pk_bf16_f32 v160, v198, v200
	v_add_f32_e32 v146, v169, v146
	s_waitcnt lgkmcnt(1)
	v_mfma_f32_32x32x16_bf16 v[80:95], v[180:183], v[96:99], v[80:95]
	v_exp_f32_e32 v180, v161
	v_exp_f32_e32 v183, v158
	v_cvt_pk_bf16_f32 v158, v184, v185
	v_cvt_pk_bf16_f32 v161, v214, v217
	v_add_f32_e32 v146, v180, v146
	v_cvt_pk_bf16_f32 v150, v169, v180
	v_add_f32_e32 v146, v183, v146
	s_nop 4
	v_max_f32_e32 v169, v81, v81
	v_max_f32_e32 v180, v80, v80
	s_waitcnt lgkmcnt(0)
; #define SBAR() __builtin_amdgcn_sched_barrier(0)
; __device__ __forceinline__ void decideSM(const f32x16& p0, const f32x16& p1, float& m_reg, float& mn, float& alpha, const float C, const float thr) {
;   float pmax = p0[0];
; #pragma unroll
;   for (int r = 1; r < 16; ++r) pmax = fmaxf(pmax, p0[r]);
; #pragma unroll
;   for (int r = 0; r < 16; ++r) pmax = fmaxf(pmax, p1[r]);
;   { auto rr = __builtin_amdgcn_permlane32_swap(__float_as_uint(pmax), __float_as_uint(pmax), false, false);
;     pmax = fmaxf(__uint_as_float(rr[0]), __uint_as_float(rr[1])); }
;   if (__builtin_expect(__all(pmax - m_reg <= thr), 1)) { mn = m_reg; alpha = 1.f; }
;   else { mn = fmaxf(m_reg, pmax); alpha = __builtin_amdgcn_exp2f((m_reg - mn) * C); m_reg = mn; }
; }
; __device__ __forceinline__ void finishSM(f32x16& p0, f32x16& p1, float alpha, float& l_reg, bf16x8& pa0, bf16x8& pa1, bf16x8& pa2, bf16x8& pa3) {
; #pragma unroll
;   for (int r = 0; r < 16; ++r) p1[r] = __builtin_amdgcn_exp2f(p1[r]);
;   float ps = 0;
; #pragma unroll
;   for (int r = 0; r < 16; ++r) ps += p0[r];
; #pragma unroll
;   for (int r = 0; r < 16; ++r) ps += p1[r];
;   { auto rr = __builtin_amdgcn_permlane32_swap(__float_as_uint(ps), __float_as_uint(ps), false, false);
;     ps = __uint_as_float(rr[0]) + __uint_as_float(rr[1]); }
;   l_reg = l_reg * alpha + ps;
;     ...
;   PK4(p0, 0, pa0); PK4(p0, 8, pa1); PK4(p1, 0, pa2); PK4(p1, 8, pa3);
;     ...
; }
; template <int D0> __device__ __forceinline__ void pv_one_sm(f32x16& od, int vb, bf16x8 pa0, bf16x8 pa1, bf16x8 pa2, bf16x8 pa3, f32x16& q0, f32x16& q1, const float C, const float mnC) {
;   const s16x4 l0 = tr_read<v_rd_off(D0, 0, 0)>(vb), h0 = tr_read<v_rd_off(D0, 0, 1)>(vb), l1 = tr_read<v_rd_off(D0, 1, 0)>(vb), h1 = tr_read<v_rd_off(D0, 1, 1)>(vb);
;   const s16x4 l2 = tr_read<v_rd_off(D0, 2, 0)>(vb), h2 = tr_read<v_rd_off(D0, 2, 1)>(vb), l3 = tr_read<v_rd_off(D0, 3, 0)>(vb), h3 = tr_read<v_rd_off(D0, 3, 1)>(vb);
;   asm volatile("s_waitcnt lgkmcnt(0)" ::: "memory"); SBAR();
;     ...
;   od = __builtin_amdgcn_mfma_f32_32x32x16_bf16(pa0, PK(l0, h0), od, 0, 0, 0);
;   od = __builtin_amdgcn_mfma_f32_32x32x16_bf16(pa1, PK(l1, h1), od, 0, 0, 0);
;   od = __builtin_amdgcn_mfma_f32_32x32x16_bf16(pa2, PK(l2, h2), od, 0, 0, 0);
;   od = __builtin_amdgcn_mfma_f32_32x32x16_bf16(pa3, PK(l3, h3), od, 0, 0, 0);
	v_mfma_f32_32x32x16_bf16 v[64:79], v[222:225], v[96:99], v[64:79]
	v_max_f32_e32 v169, v180, v169
	v_max3_f32 v169, v169, v82, v83
	v_max3_f32 v169, v169, v84, v85
	v_max3_f32 v169, v169, v86, v87
	v_max3_f32 v169, v169, v88, v89
	v_max3_f32 v169, v169, v90, v91
	v_exp_f32_e32 v222, v159
	v_max3_f32 v169, v169, v92, v93
	v_exp_f32_e32 v223, v156
	v_max3_f32 v169, v169, v94, v95
	v_exp_f32_e32 v224, v157
	s_nop 0
	v_max3_f32 v169, v169, v64, v65
	v_exp_f32_e32 v225, v154
	v_max3_f32 v169, v169, v66, v67
	v_add_f32_e32 v146, v222, v146
	v_max3_f32 v169, v169, v68, v69
	v_add_f32_e32 v146, v223, v146
	v_max3_f32 v169, v169, v70, v71
	v_add_f32_e32 v146, v224, v146
	v_max3_f32 v169, v169, v72, v73
	v_add_f32_e32 v146, v225, v146
	v_max3_f32 v169, v169, v74, v75
	v_add_f32_e32 v146, v226, v146
	v_max3_f32 v169, v169, v76, v77
	v_add_f32_e32 v146, v227, v146
	v_max3_f32 v169, v169, v78, v79
	v_add_f32_e32 v146, v228, v146
	v_mov_b32_e32 v180, v169
	v_add_f32_e32 v146, v229, v146
	s_nop 0
	v_permlane32_swap_b32_e32 v169, v180
	v_add_f32_e32 v146, v230, v146
	v_max_f32_e32 v180, v180, v180
	v_max_f32_e32 v169, v169, v169
	v_add_f32_e32 v146, v148, v146
	v_max_f32_e32 v169, v169, v180
	v_add_f32_e32 v146, v149, v146
	v_sub_f32_e32 v180, v169, v178
	v_add_f32_e32 v146, v231, v146
	v_cmp_ge_f32_e32 vcc, s56, v180
	v_max_f32_e32 v180, v178, v178
	v_add_f32_e32 v181, v232, v146
	v_max_f32_e32 v180, v180, v169
	v_mov_b32_e32 v182, v181
	s_cmp_eq_u64 vcc, exec
	v_sub_f32_e32 v169, v178, v180
	v_permlane32_swap_b32_e32 v181, v182
	s_cselect_b64 s[8:9], -1, 0
	v_mul_f32_e32 v169, 0x3dd53b94, v169
	v_cvt_pk_bf16_f32 v159, v189, v191
	v_cvt_pk_bf16_f32 v154, v215, v218
	v_cvt_pk_bf16_f32 v156, v216, v219
	v_cvt_pk_bf16_f32 v157, v220, v221
	v_cvt_pk_bf16_f32 v151, v183, v222
	v_cvt_pk_bf16_f32 v152, v223, v224
	v_cvt_pk_bf16_f32 v153, v225, v226
	v_cvt_pk_bf16_f32 v146, v227, v228
	v_cvt_pk_bf16_f32 v148, v148, v149
	v_cvt_pk_bf16_f32 v149, v231, v232
	s_add_i32 s10, s13, 0xfffe8000
	s_mov_b32 s38, s30
	s_mov_b32 s39, s31
	s_add_i32 s11, s13, 0xffff0000
	buffer_load_dwordx4 v[198:201], v170, s[28:31], s10 offen
	buffer_load_dwordx4 v[214:217], v170, s[28:31], s11 offen
	buffer_load_dwordx4 v[218:221], v171, s[36:39], s12 offen
	buffer_load_dwordx4 v[222:225], v176, s[36:39], s12 offen
	buffer_load_dwordx4 v[226:229], v177, s[36:39], s12 offen
	v_exp_f32_e32 v183, v169
	s_lshl_b32 s16, s44, 14
	v_add_u32_e32 v169, s16, v168
	ds_read_b64_tr_b16 v[230:231], v169 offset:0
	ds_read_b64_tr_b16 v[232:233], v169 offset:0x800
	ds_read_b64_tr_b16 v[234:235], v169 offset:0x1000
	ds_read_b64_tr_b16 v[236:237], v169 offset:0x1800
	ds_read_b64_tr_b16 v[238:239], v169 offset:0x2000
	ds_read_b64_tr_b16 v[240:241], v169 offset:0x2800
	ds_read_b64_tr_b16 v[242:243], v169 offset:0x3000
	ds_read_b64_tr_b16 v[244:245], v169 offset:0x3800
	s_waitcnt lgkmcnt(6)
	s_nop 0
	v_mfma_f32_32x32x16_bf16 v[0:15], v[158:161], v[230:233], v[0:15]
	ds_read_b64_tr_b16 v[230:231], v169 offset:0x200
	ds_read_b64_tr_b16 v[232:233], v169 offset:0xa00
	s_waitcnt lgkmcnt(6)
	v_mfma_f32_32x32x16_bf16 v[0:15], v[154:157], v[234:237], v[0:15]
	ds_read_b64_tr_b16 v[234:235], v169 offset:0x1200
	ds_read_b64_tr_b16 v[236:237], v169 offset:0x1a00
	s_waitcnt lgkmcnt(6)
	v_mfma_f32_32x32x16_bf16 v[0:15], v[150:153], v[238:241], v[0:15]
	ds_read_b64_tr_b16 v[238:239], v169 offset:0x2200
	ds_read_b64_tr_b16 v[240:241], v169 offset:0x2a00
	s_waitcnt lgkmcnt(6)
	v_mfma_f32_32x32x16_bf16 v[0:15], v[146:149], v[242:245], v[0:15]
	ds_read_b64_tr_b16 v[242:243], v169 offset:0x3200
	ds_read_b64_tr_b16 v[244:245], v169 offset:0x3a00
	s_waitcnt lgkmcnt(6)
	v_mfma_f32_32x32x16_bf16 v[48:63], v[158:161], v[230:233], v[48:63]
	ds_read_b64_tr_b16 v[230:231], v169 offset:0x400
	ds_read_b64_tr_b16 v[232:233], v169 offset:0xc00
	s_waitcnt lgkmcnt(6)
	v_mfma_f32_32x32x16_bf16 v[48:63], v[154:157], v[234:237], v[48:63]
	ds_read_b64_tr_b16 v[234:235], v169 offset:0x1400
	ds_read_b64_tr_b16 v[236:237], v169 offset:0x1c00
	s_waitcnt lgkmcnt(6)
	v_mfma_f32_32x32x16_bf16 v[48:63], v[150:153], v[238:241], v[48:63]
	ds_read_b64_tr_b16 v[238:239], v169 offset:0x2400
	ds_read_b64_tr_b16 v[240:241], v169 offset:0x2c00
	s_waitcnt lgkmcnt(6)
	v_mfma_f32_32x32x16_bf16 v[48:63], v[146:149], v[242:245], v[48:63]
	ds_read_b64_tr_b16 v[242:243], v169 offset:0x3400
	ds_read_b64_tr_b16 v[244:245], v169 offset:0x3c00
	s_waitcnt lgkmcnt(6)
	v_mfma_f32_32x32x16_bf16 v[32:47], v[158:161], v[230:233], v[32:47]
	ds_read_b64_tr_b16 v[230:231], v169 offset:0x600
	ds_read_b64_tr_b16 v[232:233], v169 offset:0xe00
	s_waitcnt lgkmcnt(6)
	v_mfma_f32_32x32x16_bf16 v[32:47], v[154:157], v[234:237], v[32:47]
	ds_read_b64_tr_b16 v[234:235], v169 offset:0x1600
	ds_read_b64_tr_b16 v[236:237], v169 offset:0x1e00
	s_waitcnt lgkmcnt(6)
	v_mfma_f32_32x32x16_bf16 v[32:47], v[150:153], v[238:241], v[32:47]
	ds_read_b64_tr_b16 v[238:239], v169 offset:0x2600
	ds_read_b64_tr_b16 v[240:241], v169 offset:0x2e00
	s_waitcnt lgkmcnt(6)
	v_mfma_f32_32x32x16_bf16 v[32:47], v[146:149], v[242:245], v[32:47]
	ds_read_b64_tr_b16 v[242:243], v169 offset:0x3600
	ds_read_b64_tr_b16 v[244:245], v169 offset:0x3e00
	s_waitcnt lgkmcnt(0)
	v_mfma_f32_32x32x16_bf16 v[16:31], v[158:161], v[230:233], v[16:31]
	s_waitcnt vmcnt(0)
	s_lshl_b32 s15, s51, 14
	s_mul_i32 s17, s51, 0x6400
	v_cndmask_b32_e64 v183, v183, 1.0, s[8:9]
	v_cmp_gt_f32_e32 vcc, 1.0, v183
	v_mfma_f32_32x32x16_bf16 v[16:31], v[154:157], v[234:237], v[16:31]
	v_add_u32_e32 v154, s15, v175
	s_waitcnt vmcnt(4)
	ds_write_b128 v154, v[198:201]
	s_waitcnt vmcnt(3)
	ds_write_b128 v154, v[214:217] offset:8192
	v_mfma_f32_32x32x16_bf16 v[16:31], v[150:153], v[238:241], v[16:31]
	v_add_u32_e32 v150, s17, v173
	s_waitcnt vmcnt(2)
	ds_write_b128 v150, v[218:221] offset:49152
	s_waitcnt vmcnt(1)
	ds_write_b128 v150, v[222:225] offset:49280
	s_waitcnt vmcnt(0)
	ds_write_b128 v150, v[226:229] offset:49408
	v_mfma_f32_32x32x16_bf16 v[16:31], v[146:149], v[242:245], v[16:31]
	s_cbranch_vccz .LBB0_2543
; template <int D0> __device__ __forceinline__ void pv_one_sm(f32x16& od, int vb, bf16x8 pa0, bf16x8 pa1, bf16x8 pa2, bf16x8 pa3, f32x16& q0, f32x16& q1, const float C, const float mnC) {
;     ...
;   if (D0 < 2) {
; #pragma unroll
;     for (int r = 8 * D0; r < 8 * D0 + 8; ++r) q0[r] = __builtin_amdgcn_exp2f(fmaf(q0[r], C, mnC));
;   } else {
; #pragma unroll
;     for (int r = 8 * (D0 - 2); r < 8 * (D0 - 2) + 8; ++r) q1[r] = fmaf(q1[r], C, mnC);
;   }
; }
	s_and_saveexec_b64 s[10:11], s[6:7]
	ds_write_b32 v166, v183 offset:128
	s_or_b64 exec, exec, s[10:11]
	s_waitcnt lgkmcnt(0)
	v_add_u32_e32 v158, v165, v162
	ds_read_b128 v[146:149], v158 offset:224
	ds_read_b128 v[150:153], v158 offset:192
	ds_read_b128 v[154:157], v158 offset:160
	ds_read_b128 v[158:161], v158 offset:128
	s_waitcnt lgkmcnt(3)
	v_pk_mul_f32 v[12:13], v[12:13], v[146:147]
	s_waitcnt lgkmcnt(2)
	v_pk_mul_f32 v[8:9], v[8:9], v[150:151]
	s_waitcnt lgkmcnt(1)
	v_pk_mul_f32 v[4:5], v[4:5], v[154:155]
	v_pk_mul_f32 v[14:15], v[14:15], v[148:149]
	v_pk_mul_f32 v[10:11], v[10:11], v[152:153]
	v_pk_mul_f32 v[6:7], v[6:7], v[156:157]
	s_waitcnt lgkmcnt(0)
	v_pk_mul_f32 v[2:3], v[2:3], v[160:161]
	v_pk_mul_f32 v[0:1], v[0:1], v[158:159]
	v_pk_mul_f32 v[60:61], v[60:61], v[146:147]
	v_pk_mul_f32 v[56:57], v[56:57], v[150:151]
	v_pk_mul_f32 v[52:53], v[52:53], v[154:155]
	v_pk_mul_f32 v[62:63], v[62:63], v[148:149]
	v_pk_mul_f32 v[58:59], v[58:59], v[152:153]
	v_pk_mul_f32 v[54:55], v[54:55], v[156:157]
	v_pk_mul_f32 v[50:51], v[50:51], v[160:161]
	v_pk_mul_f32 v[48:49], v[48:49], v[158:159]
	v_pk_mul_f32 v[44:45], v[44:45], v[146:147]
	v_pk_mul_f32 v[40:41], v[40:41], v[150:151]
	v_pk_mul_f32 v[36:37], v[36:37], v[154:155]
	v_pk_mul_f32 v[46:47], v[46:47], v[148:149]
	v_pk_mul_f32 v[42:43], v[42:43], v[152:153]
	v_pk_mul_f32 v[38:39], v[38:39], v[156:157]
	v_pk_mul_f32 v[34:35], v[34:35], v[160:161]
	v_pk_mul_f32 v[32:33], v[32:33], v[158:159]
	v_pk_mul_f32 v[28:29], v[28:29], v[146:147]
	v_pk_mul_f32 v[24:25], v[24:25], v[150:151]
	v_pk_mul_f32 v[20:21], v[20:21], v[154:155]
	v_pk_mul_f32 v[30:31], v[30:31], v[148:149]
	v_pk_mul_f32 v[26:27], v[26:27], v[152:153]
	v_pk_mul_f32 v[22:23], v[22:23], v[156:157]
	v_pk_mul_f32 v[18:19], v[18:19], v[160:161]
	v_pk_mul_f32 v[16:17], v[16:17], v[158:159]
.LBB0_2543:
	v_cndmask_b32_e64 v178, v180, v178, s[8:9]
	v_mul_f32_e32 v154, 0xbdd53b94, v178
	v_fmamk_f32 v80, v80, 0x3dd53b94, v154
	v_exp_f32_e32 v155, v80
	v_fmamk_f32 v80, v81, 0x3dd53b94, v154
	v_exp_f32_e32 v156, v80
	v_fmamk_f32 v80, v82, 0x3dd53b94, v154
	v_exp_f32_e32 v157, v80
	v_fmamk_f32 v80, v83, 0x3dd53b94, v154
	v_exp_f32_e32 v159, v80
	v_fmamk_f32 v80, v84, 0x3dd53b94, v154
	v_exp_f32_e32 v160, v80
	v_fmamk_f32 v80, v85, 0x3dd53b94, v154
	v_exp_f32_e32 v161, v80
	v_fmamk_f32 v80, v86, 0x3dd53b94, v154
	v_exp_f32_e32 v180, v80
	v_fmamk_f32 v80, v87, 0x3dd53b94, v154
	v_exp_f32_e32 v189, v80
	v_fmamk_f32 v80, v88, 0x3dd53b94, v154
	v_exp_f32_e32 v191, v80
	v_fmamk_f32 v80, v89, 0x3dd53b94, v154
	v_exp_f32_e32 v198, v80
	v_fmamk_f32 v80, v90, 0x3dd53b94, v154
	v_exp_f32_e32 v199, v80
	v_fmamk_f32 v80, v91, 0x3dd53b94, v154
	v_exp_f32_e32 v200, v80
	v_fmamk_f32 v80, v92, 0x3dd53b94, v154
	v_exp_f32_e32 v201, v80
	v_fmamk_f32 v80, v93, 0x3dd53b94, v154
	v_exp_f32_e32 v214, v80
	v_fmamk_f32 v80, v94, 0x3dd53b94, v154
	v_exp_f32_e32 v215, v80
	v_fmamk_f32 v80, v95, 0x3dd53b94, v154
	v_fmamk_f32 v184, v66, 0x3dd53b94, v154
	v_fmamk_f32 v185, v68, 0x3dd53b94, v154
	v_exp_f32_e32 v216, v80
	v_fmamk_f32 v158, v64, 0x3dd53b94, v154
	v_fmamk_f32 v217, v70, 0x3dd53b94, v154
	v_fmamk_f32 v218, v65, 0x3dd53b94, v154
	v_fmamk_f32 v219, v67, 0x3dd53b94, v154
	v_fmamk_f32 v220, v69, 0x3dd53b94, v154
	v_fmamk_f32 v221, v71, 0x3dd53b94, v154
	v_fmamk_f32 v222, v72, 0x3dd53b94, v154
	v_fmamk_f32 v223, v73, 0x3dd53b94, v154
	v_fmamk_f32 v224, v74, 0x3dd53b94, v154
	v_fmamk_f32 v225, v75, 0x3dd53b94, v154
	v_fmamk_f32 v226, v76, 0x3dd53b94, v154
	v_fmamk_f32 v227, v77, 0x3dd53b94, v154
	v_fmamk_f32 v228, v78, 0x3dd53b94, v154
	v_fmac_f32_e32 v154, 0x3dd53b94, v79
	s_waitcnt lgkmcnt(0)
	s_barrier
	v_add_u32_e32 v229, s17, v174
	ds_read_b128 v[64:67], v229 offset:61952
	ds_read_b128 v[68:71], v229 offset:49152
	ds_read_b128 v[146:149], v229 offset:49184
	ds_read_b128 v[150:153], v229 offset:61984
	ds_read_b128 v[246:249], v229 offset:49216
	ds_read_b128 v[250:253], v229 offset:62016
	v_exp_f32_e32 v217, v217
	s_waitcnt lgkmcnt(4)
	v_mfma_f32_32x32x16_bf16 v[80:95], v[68:71], v[140:143], 0
	v_mfma_f32_32x32x16_bf16 v[64:79], v[64:67], v[140:143], 0
	s_waitcnt lgkmcnt(3)
	v_mfma_f32_32x32x16_bf16 v[80:95], v[146:149], v[136:139], v[80:95]
	s_waitcnt lgkmcnt(2)
	v_mfma_f32_32x32x16_bf16 v[64:79], v[150:153], v[136:139], v[64:79]
	ds_read_b128 v[146:149], v229 offset:49248
	ds_read_b128 v[150:153], v229 offset:62048
	s_waitcnt lgkmcnt(3)
	v_mfma_f32_32x32x16_bf16 v[80:95], v[246:249], v[132:135], v[80:95]
	s_waitcnt lgkmcnt(2)
	v_mfma_f32_32x32x16_bf16 v[64:79], v[250:253], v[132:135], v[64:79]
	ds_read_b128 v[246:249], v229 offset:49280
	ds_read_b128 v[250:253], v229 offset:62080
	s_waitcnt lgkmcnt(3)
	v_mfma_f32_32x32x16_bf16 v[80:95], v[146:149], v[128:131], v[80:95]
	s_waitcnt lgkmcnt(2)
	v_mfma_f32_32x32x16_bf16 v[64:79], v[150:153], v[128:131], v[64:79]
	ds_read_b128 v[146:149], v229 offset:49312
	ds_read_b128 v[150:153], v229 offset:62112
	s_waitcnt lgkmcnt(3)
	v_mfma_f32_32x32x16_bf16 v[80:95], v[246:249], v[124:127], v[80:95]
	s_waitcnt lgkmcnt(2)
	v_mfma_f32_32x32x16_bf16 v[64:79], v[250:253], v[124:127], v[64:79]
	ds_read_b128 v[246:249], v229 offset:49344
	ds_read_b128 v[250:253], v229 offset:62144
	s_waitcnt lgkmcnt(3)
	v_mfma_f32_32x32x16_bf16 v[80:95], v[146:149], v[120:123], v[80:95]
	s_waitcnt lgkmcnt(2)
	v_mfma_f32_32x32x16_bf16 v[64:79], v[150:153], v[120:123], v[64:79]
	ds_read_b128 v[146:149], v229 offset:49376
	ds_read_b128 v[150:153], v229 offset:62176
	s_waitcnt lgkmcnt(3)
	v_mfma_f32_32x32x16_bf16 v[80:95], v[246:249], v[116:119], v[80:95]
	s_waitcnt lgkmcnt(2)
; #define PK4(P, BASE, OUT) do { u32x4 w = {cvtb(P[BASE + 0], P[BASE + 1]), cvtb(P[BASE + 2], P[BASE + 3]), \
;     cvtb(P[BASE + 4], P[BASE + 5]), cvtb(P[BASE + 6], P[BASE + 7])}; OUT = *reinterpret_cast<bf16x8*>(&w); } while (0)
; __device__ __forceinline__ void decideSM(const f32x16& p0, const f32x16& p1, float& m_reg, float& mn, float& alpha, const float C, const float thr) {
;   float pmax = p0[0];
; #pragma unroll
;   for (int r = 1; r < 16; ++r) pmax = fmaxf(pmax, p0[r]);
; #pragma unroll
;   for (int r = 0; r < 16; ++r) pmax = fmaxf(pmax, p1[r]);
;   { auto rr = __builtin_amdgcn_permlane32_swap(__float_as_uint(pmax), __float_as_uint(pmax), false, false);
;     pmax = fmaxf(__uint_as_float(rr[0]), __uint_as_float(rr[1])); }
;   if (__builtin_expect(__all(pmax - m_reg <= thr), 1)) { mn = m_reg; alpha = 1.f; }
;   else { mn = fmaxf(m_reg, pmax); alpha = __builtin_amdgcn_exp2f((m_reg - mn) * C); m_reg = mn; }
; }
; __device__ __forceinline__ void finishSM(f32x16& p0, f32x16& p1, float alpha, float& l_reg, bf16x8& pa0, bf16x8& pa1, bf16x8& pa2, bf16x8& pa3) {
; #pragma unroll
;   for (int r = 0; r < 16; ++r) p1[r] = __builtin_amdgcn_exp2f(p1[r]);
;   float ps = 0;
; #pragma unroll
;   for (int r = 0; r < 16; ++r) ps += p0[r];
; #pragma unroll
;   for (int r = 0; r < 16; ++r) ps += p1[r];
;   { auto rr = __builtin_amdgcn_permlane32_swap(__float_as_uint(ps), __float_as_uint(ps), false, false);
;     ps = __uint_as_float(rr[0]) + __uint_as_float(rr[1]); }
;   l_reg = l_reg * alpha + ps;
;     ...
;   PK4(p0, 0, pa0); PK4(p0, 8, pa1); PK4(p1, 0, pa2); PK4(p1, 8, pa3);
;     ...
; }
; template <int NQK>
; __device__ __forceinline__ void qkt(f32x16& p0, f32x16& p1, const char* Ks, const bf16x8* qr, int r32, int hi) {
;   constexpr int KROW = NQK * 32 + 16;
;   p0 = f32x16{}; p1 = f32x16{};
; #pragma unroll
;   for (int d0 = 0; d0 < NQK; ++d0) { const int cb = (d0 * 16 + hi * 8) * 2;
;     bf16x8 b0 = *reinterpret_cast<const bf16x8*>(Ks + r32 * KROW + cb);
;     bf16x8 b1 = *reinterpret_cast<const bf16x8*>(Ks + (32 + r32) * KROW + cb);
;     p0 = __builtin_amdgcn_mfma_f32_32x32x16_bf16(b0, qr[d0], p0, 0, 0, 0);
;     p1 = __builtin_amdgcn_mfma_f32_32x32x16_bf16(b1, qr[d0], p1, 0, 0, 0); }
	v_mfma_f32_32x32x16_bf16 v[64:79], v[250:253], v[116:119], v[64:79]
	ds_read_b128 v[246:249], v229 offset:49408
	ds_read_b128 v[250:253], v229 offset:62208
	s_waitcnt lgkmcnt(3)
	v_mfma_f32_32x32x16_bf16 v[80:95], v[146:149], v[112:115], v[80:95]
	s_waitcnt lgkmcnt(2)
	v_mfma_f32_32x32x16_bf16 v[64:79], v[150:153], v[112:115], v[64:79]
	ds_read_b128 v[146:149], v229 offset:49440
	ds_read_b128 v[150:153], v229 offset:62240
	s_waitcnt lgkmcnt(3)
	v_mfma_f32_32x32x16_bf16 v[80:95], v[246:249], v[108:111], v[80:95]
	s_waitcnt lgkmcnt(2)
	v_mfma_f32_32x32x16_bf16 v[64:79], v[250:253], v[108:111], v[64:79]
	ds_read_b128 v[246:249], v229 offset:49472
	ds_read_b128 v[250:253], v229 offset:62272
	s_waitcnt lgkmcnt(3)
	v_mfma_f32_32x32x16_bf16 v[80:95], v[146:149], v[104:107], v[80:95]
	s_waitcnt lgkmcnt(2)
	v_mfma_f32_32x32x16_bf16 v[64:79], v[150:153], v[104:107], v[64:79]
	ds_read_b128 v[146:149], v229 offset:49504
	ds_read_b128 v[150:153], v229 offset:62304
	s_waitcnt lgkmcnt(3)
	v_mfma_f32_32x32x16_bf16 v[80:95], v[246:249], v[100:103], v[80:95]
	s_waitcnt lgkmcnt(2)
	v_mfma_f32_32x32x16_bf16 v[64:79], v[250:253], v[100:103], v[64:79]
	s_waitcnt lgkmcnt(1)
	v_mfma_f32_32x32x16_bf16 v[80:95], v[146:149], v[96:99], v[80:95]
	v_exp_f32_e32 v146, v158
	v_exp_f32_e32 v147, v218
	v_exp_f32_e32 v148, v184
	v_exp_f32_e32 v149, v219
	v_exp_f32_e32 v218, v221
	v_exp_f32_e32 v219, v222
	v_exp_f32_e32 v221, v224
	s_waitcnt lgkmcnt(0)
	v_mfma_f32_32x32x16_bf16 v[64:79], v[150:153], v[96:99], v[64:79]
	v_add_f32_e32 v150, 0, v155
	v_add_f32_e32 v150, v156, v150
	v_add_f32_e32 v150, v157, v150
	v_add_f32_e32 v150, v159, v150
	v_add_f32_e32 v150, v160, v150
	v_add_f32_e32 v150, v161, v150
	v_add_f32_e32 v150, v180, v150
	v_add_f32_e32 v150, v189, v150
	v_add_f32_e32 v150, v191, v150
	v_cvt_pk_bf16_f32 v160, v160, v161
	v_cvt_pk_bf16_f32 v161, v180, v189
	v_max_f32_e32 v180, v81, v81
	v_max_f32_e32 v189, v80, v80
	v_add_f32_e32 v150, v198, v150
	v_max_f32_e32 v180, v189, v180
	v_add_f32_e32 v150, v199, v150
	v_max3_f32 v180, v180, v82, v83
	v_add_f32_e32 v150, v200, v150
	v_max3_f32 v180, v180, v84, v85
	v_add_f32_e32 v150, v201, v150
	v_max3_f32 v180, v180, v86, v87
	v_add_f32_e32 v150, v214, v150
	v_max3_f32 v180, v180, v88, v89
	v_add_f32_e32 v150, v215, v150
	v_max3_f32 v180, v180, v90, v91
	v_add_f32_e32 v150, v216, v150
	v_max3_f32 v180, v180, v92, v93
	v_exp_f32_e32 v152, v185
	v_add_f32_e32 v150, v146, v150
	v_max3_f32 v180, v180, v94, v95
	v_exp_f32_e32 v153, v220
	v_add_f32_e32 v150, v147, v150
	v_max3_f32 v180, v180, v64, v65
	v_add_f32_e32 v150, v148, v150
	v_max3_f32 v180, v180, v66, v67
	v_add_f32_e32 v150, v149, v150
	v_max3_f32 v180, v180, v68, v69
	v_add_f32_e32 v150, v152, v150
	v_max3_f32 v180, v180, v70, v71
	v_exp_f32_e32 v220, v223
	v_add_f32_e32 v150, v153, v150
	v_max3_f32 v180, v180, v72, v73
	v_add_f32_e32 v150, v217, v150
	v_max3_f32 v180, v180, v74, v75
	v_exp_f32_e32 v222, v225
	v_add_f32_e32 v150, v218, v150
	v_max3_f32 v180, v180, v76, v77
	v_exp_f32_e32 v223, v226
	v_add_f32_e32 v150, v219, v150
	v_max3_f32 v180, v180, v78, v79
	v_exp_f32_e32 v224, v227
	v_add_f32_e32 v150, v220, v150
	v_mov_b32_e32 v189, v180
	v_exp_f32_e32 v225, v228
	v_add_f32_e32 v150, v221, v150
	v_permlane32_swap_b32_e32 v180, v189
	v_exp_f32_e32 v226, v154
	v_add_f32_e32 v150, v222, v150
	v_max_f32_e32 v189, v189, v189
	v_max_f32_e32 v180, v180, v180
	v_add_f32_e32 v150, v223, v150
	v_max_f32_e32 v180, v180, v189
	v_add_f32_e32 v150, v224, v150
	v_sub_f32_e32 v189, v180, v178
	v_add_f32_e32 v150, v225, v150
	v_cmp_ge_f32_e32 vcc, s56, v189
	v_max_f32_e32 v189, v178, v178
	v_add_f32_e32 v184, v226, v150
	v_max_f32_e32 v189, v189, v180
	v_mov_b32_e32 v185, v184
	s_cmp_eq_u64 vcc, exec
	v_sub_f32_e32 v180, v178, v189
	v_permlane32_swap_b32_e32 v184, v185
	s_cselect_b64 s[8:9], -1, 0
	v_mul_f32_e32 v180, 0x3dd53b94, v180
	v_cvt_pk_bf16_f32 v158, v155, v156
	v_cvt_pk_bf16_f32 v159, v157, v159
	v_cvt_pk_bf16_f32 v154, v191, v198
	v_cvt_pk_bf16_f32 v155, v199, v200
	v_cvt_pk_bf16_f32 v156, v201, v214
	v_cvt_pk_bf16_f32 v157, v215, v216
	v_cvt_pk_bf16_f32 v150, v146, v147
	v_cvt_pk_bf16_f32 v151, v148, v149
	v_cvt_pk_bf16_f32 v152, v152, v153
	v_cvt_pk_bf16_f32 v153, v217, v218
	v_cvt_pk_bf16_f32 v146, v219, v220
	v_cvt_pk_bf16_f32 v147, v221, v222
	v_cvt_pk_bf16_f32 v148, v223, v224
	v_cvt_pk_bf16_f32 v149, v225, v226
	s_add_i32 s10, s13, 0xffff8000
	s_add_i32 s11, s12, 0x18000
	s_mov_b32 s38, s30
	s_mov_b32 s39, s31
	buffer_load_dwordx4 v[198:201], v170, s[28:31], s10 offen
	buffer_load_dwordx4 v[214:217], v170, s[28:31], s13 offen
	buffer_load_dwordx4 v[218:221], v171, s[36:39], s11 offen
	buffer_load_dwordx4 v[222:225], v176, s[36:39], s11 offen
	buffer_load_dwordx4 v[226:229], v177, s[36:39], s11 offen
	v_exp_f32_e32 v180, v180
	v_lshl_add_u32 v191, s14, 14, v168
	ds_read_b64_tr_b16 v[230:231], v191 offset:0
	ds_read_b64_tr_b16 v[232:233], v191 offset:0x800
	ds_read_b64_tr_b16 v[234:235], v191 offset:0x1000
	ds_read_b64_tr_b16 v[236:237], v191 offset:0x1800
	ds_read_b64_tr_b16 v[238:239], v191 offset:0x2000
	ds_read_b64_tr_b16 v[240:241], v191 offset:0x2800
	ds_read_b64_tr_b16 v[242:243], v191 offset:0x3000
	ds_read_b64_tr_b16 v[244:245], v191 offset:0x3800
	s_waitcnt lgkmcnt(6)
; #define SBAR() __builtin_amdgcn_sched_barrier(0)
; template <int D0> __device__ __forceinline__ void pv_one_sm(f32x16& od, int vb, bf16x8 pa0, bf16x8 pa1, bf16x8 pa2, bf16x8 pa3, f32x16& q0, f32x16& q1, const float C, const float mnC) {
;   const s16x4 l0 = tr_read<v_rd_off(D0, 0, 0)>(vb), h0 = tr_read<v_rd_off(D0, 0, 1)>(vb), l1 = tr_read<v_rd_off(D0, 1, 0)>(vb), h1 = tr_read<v_rd_off(D0, 1, 1)>(vb);
;   const s16x4 l2 = tr_read<v_rd_off(D0, 2, 0)>(vb), h2 = tr_read<v_rd_off(D0, 2, 1)>(vb), l3 = tr_read<v_rd_off(D0, 3, 0)>(vb), h3 = tr_read<v_rd_off(D0, 3, 1)>(vb);
;   asm volatile("s_waitcnt lgkmcnt(0)" ::: "memory"); SBAR();
;     ...
;   od = __builtin_amdgcn_mfma_f32_32x32x16_bf16(pa0, PK(l0, h0), od, 0, 0, 0);
;   od = __builtin_amdgcn_mfma_f32_32x32x16_bf16(pa1, PK(l1, h1), od, 0, 0, 0);
;   od = __builtin_amdgcn_mfma_f32_32x32x16_bf16(pa2, PK(l2, h2), od, 0, 0, 0);
;   od = __builtin_amdgcn_mfma_f32_32x32x16_bf16(pa3, PK(l3, h3), od, 0, 0, 0);
	s_nop 0
	v_mfma_f32_32x32x16_bf16 v[0:15], v[158:161], v[230:233], v[0:15]
	ds_read_b64_tr_b16 v[230:231], v191 offset:0x200
	ds_read_b64_tr_b16 v[232:233], v191 offset:0xa00
	s_waitcnt lgkmcnt(6)
	v_mfma_f32_32x32x16_bf16 v[0:15], v[154:157], v[234:237], v[0:15]
	ds_read_b64_tr_b16 v[234:235], v191 offset:0x1200
	ds_read_b64_tr_b16 v[236:237], v191 offset:0x1a00
	s_waitcnt lgkmcnt(6)
	v_mfma_f32_32x32x16_bf16 v[0:15], v[150:153], v[238:241], v[0:15]
	ds_read_b64_tr_b16 v[238:239], v191 offset:0x2200
	ds_read_b64_tr_b16 v[240:241], v191 offset:0x2a00
	s_waitcnt lgkmcnt(6)
	v_mfma_f32_32x32x16_bf16 v[0:15], v[146:149], v[242:245], v[0:15]
	ds_read_b64_tr_b16 v[242:243], v191 offset:0x3200
	ds_read_b64_tr_b16 v[244:245], v191 offset:0x3a00
	s_waitcnt lgkmcnt(6)
	v_mfma_f32_32x32x16_bf16 v[48:63], v[158:161], v[230:233], v[48:63]
	ds_read_b64_tr_b16 v[230:231], v191 offset:0x400
	ds_read_b64_tr_b16 v[232:233], v191 offset:0xc00
	s_waitcnt lgkmcnt(6)
	v_mfma_f32_32x32x16_bf16 v[48:63], v[154:157], v[234:237], v[48:63]
	ds_read_b64_tr_b16 v[234:235], v191 offset:0x1400
	ds_read_b64_tr_b16 v[236:237], v191 offset:0x1c00
	s_waitcnt lgkmcnt(6)
	v_mfma_f32_32x32x16_bf16 v[48:63], v[150:153], v[238:241], v[48:63]
	ds_read_b64_tr_b16 v[238:239], v191 offset:0x2400
	ds_read_b64_tr_b16 v[240:241], v191 offset:0x2c00
	s_waitcnt lgkmcnt(6)
	v_mfma_f32_32x32x16_bf16 v[48:63], v[146:149], v[242:245], v[48:63]
	ds_read_b64_tr_b16 v[242:243], v191 offset:0x3400
	ds_read_b64_tr_b16 v[244:245], v191 offset:0x3c00
	s_waitcnt lgkmcnt(6)
	v_mfma_f32_32x32x16_bf16 v[32:47], v[158:161], v[230:233], v[32:47]
	ds_read_b64_tr_b16 v[230:231], v191 offset:0x600
	ds_read_b64_tr_b16 v[232:233], v191 offset:0xe00
	s_waitcnt lgkmcnt(6)
	v_mfma_f32_32x32x16_bf16 v[32:47], v[154:157], v[234:237], v[32:47]
	ds_read_b64_tr_b16 v[234:235], v191 offset:0x1600
	ds_read_b64_tr_b16 v[236:237], v191 offset:0x1e00
	s_waitcnt lgkmcnt(6)
	v_mfma_f32_32x32x16_bf16 v[32:47], v[150:153], v[238:241], v[32:47]
	ds_read_b64_tr_b16 v[238:239], v191 offset:0x2600
	ds_read_b64_tr_b16 v[240:241], v191 offset:0x2e00
	s_waitcnt lgkmcnt(6)
	v_mfma_f32_32x32x16_bf16 v[32:47], v[146:149], v[242:245], v[32:47]
	ds_read_b64_tr_b16 v[242:243], v191 offset:0x3600
	ds_read_b64_tr_b16 v[244:245], v191 offset:0x3e00
	s_waitcnt lgkmcnt(0)
	v_mfma_f32_32x32x16_bf16 v[16:31], v[158:161], v[230:233], v[16:31]
	s_waitcnt vmcnt(0)
	v_cndmask_b32_e64 v180, v180, 1.0, s[8:9]
	v_cmp_gt_f32_e32 vcc, 1.0, v180
	v_mfma_f32_32x32x16_bf16 v[16:31], v[154:157], v[234:237], v[16:31]
	v_add_u32_e32 v154, s16, v175
	s_mul_i32 s16, s44, 0x6400
	s_waitcnt vmcnt(4)
	ds_write_b128 v154, v[198:201]
	s_waitcnt vmcnt(3)
	ds_write_b128 v154, v[214:217] offset:8192
	v_mfma_f32_32x32x16_bf16 v[16:31], v[150:153], v[238:241], v[16:31]
	v_add_u32_e32 v150, s16, v173
	s_waitcnt vmcnt(2)
	ds_write_b128 v150, v[218:221] offset:49152
	s_waitcnt vmcnt(1)
	ds_write_b128 v150, v[222:225] offset:49280
	s_waitcnt vmcnt(0)
	ds_write_b128 v150, v[226:229] offset:49408
	v_mfma_f32_32x32x16_bf16 v[16:31], v[146:149], v[242:245], v[16:31]
	s_cbranch_vccz .LBB0_2547
	s_and_saveexec_b64 s[10:11], s[6:7]
	ds_write_b32 v166, v180 offset:128
	s_or_b64 exec, exec, s[10:11]
	s_waitcnt lgkmcnt(0)
	v_add_u32_e32 v158, v165, v162
	ds_read_b128 v[146:149], v158 offset:224
	ds_read_b128 v[150:153], v158 offset:192
	ds_read_b128 v[154:157], v158 offset:160
	ds_read_b128 v[158:161], v158 offset:128
	s_waitcnt lgkmcnt(3)
	v_pk_mul_f32 v[12:13], v[12:13], v[146:147]
	s_waitcnt lgkmcnt(2)
	v_pk_mul_f32 v[8:9], v[8:9], v[150:151]
	s_waitcnt lgkmcnt(1)
	v_pk_mul_f32 v[4:5], v[4:5], v[154:155]
	v_pk_mul_f32 v[14:15], v[14:15], v[148:149]
	v_pk_mul_f32 v[10:11], v[10:11], v[152:153]
	v_pk_mul_f32 v[6:7], v[6:7], v[156:157]
	s_waitcnt lgkmcnt(0)
	v_pk_mul_f32 v[2:3], v[2:3], v[160:161]
	v_pk_mul_f32 v[0:1], v[0:1], v[158:159]
	v_pk_mul_f32 v[60:61], v[60:61], v[146:147]
	v_pk_mul_f32 v[56:57], v[56:57], v[150:151]
	v_pk_mul_f32 v[52:53], v[52:53], v[154:155]
	v_pk_mul_f32 v[62:63], v[62:63], v[148:149]
	v_pk_mul_f32 v[58:59], v[58:59], v[152:153]
	v_pk_mul_f32 v[54:55], v[54:55], v[156:157]
	v_pk_mul_f32 v[50:51], v[50:51], v[160:161]
	v_pk_mul_f32 v[48:49], v[48:49], v[158:159]
	v_pk_mul_f32 v[44:45], v[44:45], v[146:147]
	v_pk_mul_f32 v[40:41], v[40:41], v[150:151]
	v_pk_mul_f32 v[36:37], v[36:37], v[154:155]
	v_pk_mul_f32 v[46:47], v[46:47], v[148:149]
	v_pk_mul_f32 v[42:43], v[42:43], v[152:153]
	v_pk_mul_f32 v[38:39], v[38:39], v[156:157]
	v_pk_mul_f32 v[34:35], v[34:35], v[160:161]
	v_pk_mul_f32 v[32:33], v[32:33], v[158:159]
	v_pk_mul_f32 v[28:29], v[28:29], v[146:147]
	v_pk_mul_f32 v[24:25], v[24:25], v[150:151]
	v_pk_mul_f32 v[20:21], v[20:21], v[154:155]
	v_pk_mul_f32 v[30:31], v[30:31], v[148:149]
	v_pk_mul_f32 v[26:27], v[26:27], v[152:153]
	v_pk_mul_f32 v[22:23], v[22:23], v[156:157]
	v_pk_mul_f32 v[18:19], v[18:19], v[160:161]
	v_pk_mul_f32 v[16:17], v[16:17], v[158:159]
